# RG-LRU phase start: first unit's conv-input loads issued before the gate-fragment staging is waited for (prologue de-serialisation)
# baseline (speedup 1.0000x reference)
; #define LAS __attribute__((address_space(3)))
; __device__ __forceinline__ void lru_phase(const Ptrs& P, LAS unsigned char* lds, int G, int wave, int lane, int tid) {
;     ...
;     { const int hd0 = blockIdx.x & 15;
;       const v4u* src = (const v4u*)(WGF + (size_t)hd0 * 18432); LAS v4u* dst = (LAS v4u*)(lds + L_WGF);
;       for (int i = tid; i < 2304; i += NT) dst[i] = src[i];
;       const f32x4* ps = (const f32x4*)(PAR + hd0 * 640); LAS f32x4* pd = (LAS f32x4*)(lds + L_PAR);
;       if (tid < 160) pd[tid] = ps[tid]; }
;     __syncthreads();
;     v2u raw[10][4];
;     ...
;     if ((int)blockIdx.x < 64 * NCHUNK) LRU_LOAD_RAW((int)blockIdx.x);
.LBB0_290:
	s_cmp_lt_i32 s56, 3
	s_cselect_b64 s[4:5], -1, 0
	s_and_b64 s[8:9], s[4:5], s[2:3]
	s_andn2_b64 vcc, exec, s[8:9]
	v_lshlrev_b32_e32 v186, 4, v184
	s_cbranch_vccnz .LBB0_327
	s_and_b32 s6, s33, 15
	s_mul_i32 s2, s6, 0x9000
	s_add_u32 s2, s54, s2
	v_mov_b32_e32 v187, 0
	s_addc_u32 s3, s55, 0
	v_lshl_add_u64 v[0:1], s[2:3], 0, v[186:187]
	s_mov_b64 s[2:3], 0x1600000
	v_add_u32_e32 v2, 0xfffffe00, v184
	v_add_u32_e32 v70, 0, v186
	v_lshl_add_u64 v[0:1], v[0:1], 0, s[2:3]
	s_mov_b64 s[2:3], 0
	s_mov_b64 s[4:5], 0x2000
	s_movk_i32 s7, 0x6ff
.LBB0_292:
	s_movk_i32 s7, 0x100
	v_cmp_gt_u32_e64 s[96:97], s7, v184
	s_movk_i32 s7, 0xa0
	v_cmp_gt_u32_e64 s[98:99], s7, v184
	global_load_dwordx4 v[44:47], v[0:1], off
	v_lshl_add_u64 v[0:1], v[0:1], 0, s[4:5]
	global_load_dwordx4 v[48:51], v[0:1], off
	v_lshl_add_u64 v[0:1], v[0:1], 0, s[4:5]
	global_load_dwordx4 v[52:55], v[0:1], off
	v_lshl_add_u64 v[0:1], v[0:1], 0, s[4:5]
	global_load_dwordx4 v[56:59], v[0:1], off
	v_lshl_add_u64 v[0:1], v[0:1], 0, s[4:5]
	s_and_saveexec_b64 s[2:3], s[96:97]
	s_cbranch_execz .Lp2_stage_a
	global_load_dwordx4 v[60:63], v[0:1], off
.Lp2_stage_a:
	s_or_b64 exec, exec, s[2:3]
	s_and_saveexec_b64 s[2:3], s[98:99]
	s_cbranch_execz .Lp2_stage_b
	s_mul_i32 s4, s6, 0xa00
	s_add_u32 s4, s54, s4
	s_addc_u32 s5, s55, 0
	s_add_u32 s4, s4, 0x1d0000
	s_addc_u32 s5, s5, 0
	v_lshl_add_u64 v[24:25], s[4:5], 0, v[186:187]
	global_load_dwordx4 v[66:69], v[24:25], off
.Lp2_stage_b:
	s_or_b64 exec, exec, s[2:3]
	s_cmpk_gt_i32 s33, 0x3ff
	s_cbranch_scc1 .Lp2_nounit
	s_add_u32 s10, s54, 0x3800000
	s_addc_u32 s11, s55, 0
	s_lshl_b32 s2, s33, 2
	s_and_b32 s2, s2, 0xffffff00
	s_lshl_b32 s26, s63, 5
	v_and_b32_e32 v185, 31, v184
	s_add_i32 s2, s26, s2
	v_add_u32_e32 v4, -3, v185
	s_add_u32 s12, s54, 0x1780000
	v_add_u32_e32 v5, s2, v4
	s_addc_u32 s13, s55, 0
	s_and_b32 s4, s68, 0x180
	v_and_b32_e32 v187, 32, v184
	v_mov_b32_e32 v3, 0
	v_cmp_lt_i32_e32 vcc, -1, v5
	v_mov_b64_e32 v[0:1], s[12:13]
	s_and_saveexec_b64 s[2:3], vcc
	v_lshrrev_b32_e32 v0, 5, v5
	v_add_u32_e32 v0, s4, v0
	v_lshl_or_b32 v0, v0, 4, s6
	v_mul_lo_u32 v2, v0, 10
	v_lshlrev_b64 v[0:1], 6, v[2:3]
	v_and_or_b32 v0, v4, 31, v0
	v_or_b32_e32 v0, v0, v187
	v_lshl_add_u64 v[0:1], v[0:1], 3, s[10:11]
	s_or_b64 exec, exec, s[2:3]
	global_load_dwordx2 v[40:41], v[0:1], off offset:1024
	global_load_dwordx2 v[42:43], v[0:1], off offset:1536
	global_load_dwordx2 v[76:77], v[0:1], off offset:2048
	global_load_dwordx2 v[78:79], v[0:1], off offset:2560
	global_load_dwordx2 v[112:113], v[0:1], off offset:3072
	global_load_dwordx2 v[28:29], v[0:1], off offset:3584
	v_add_co_u32_e32 v2, vcc, 0x1000, v0
	s_nop 1
	v_addc_co_u32_e32 v3, vcc, 0, v1, vcc
	global_load_dwordx2 v[36:37], v[0:1], off
	global_load_dwordx2 v[38:39], v[0:1], off offset:512
	global_load_dwordx2 v[20:21], v[2:3], off
	global_load_dwordx2 v[16:17], v[2:3], off offset:512
	v_cmp_lt_i32_e32 vcc, -2, v5
	v_mov_b64_e32 v[0:1], s[12:13]
	s_and_saveexec_b64 s[2:3], vcc
	s_cbranch_execz .LBB0_300
	v_add_u32_e32 v2, 1, v5
	v_lshrrev_b32_e32 v0, 5, v2
	v_add_u32_e32 v0, s4, v0
	v_lshl_or_b32 v0, v0, 4, s6
	v_mul_lo_u32 v0, v0, 10
	v_mov_b32_e32 v1, 0
	v_lshlrev_b64 v[0:1], 6, v[0:1]
	v_and_or_b32 v0, v2, 31, v0
	v_or_b32_e32 v0, v0, v187
	v_lshl_add_u64 v[0:1], v[0:1], 3, s[10:11]

; #define LAS __attribute__((address_space(3)))
; __device__ __forceinline__ float ex2(float x) { return __builtin_amdgcn_exp2f(x); }
; __device__ __forceinline__ void lru_phase(const Ptrs& P, LAS unsigned char* lds, int G, int wave, int lane, int tid) {
;     ...
;     { const int hd0 = blockIdx.x & 15;
;       const v4u* src = (const v4u*)(WGF + (size_t)hd0 * 18432); LAS v4u* dst = (LAS v4u*)(lds + L_WGF);
;       for (int i = tid; i < 2304; i += NT) dst[i] = src[i];
;       const f32x4* ps = (const f32x4*)(PAR + hd0 * 640); LAS f32x4* pd = (LAS f32x4*)(lds + L_PAR);
;       if (tid < 160) pd[tid] = ps[tid]; }
;     __syncthreads();
;     v2u raw[10][4];
;     ...
;     if ((int)blockIdx.x < 64 * NCHUNK) LRU_LOAD_RAW((int)blockIdx.x);
;     ...
;         const v4u xone_u = {hh == 0 ? 0x3F80u : 0u, 0u, 0u, 0u}; const bf16x8 xone = __builtin_bit_cast(bf16x8, xone_u);
; #pragma unroll
;         for (int mt = 0; mt < 3; ++mt) {
;             f32x16 gr, gi;
; #pragma unroll
;             for (int i = 0; i < 16; ++i) { gr[i] = 0.f; gi[i] = 0.f; }
;             const LAS bf16x8* wa = (const LAS bf16x8*)(lds + L_WGF) + (size_t)(mt * 6) * 64 + lane;
;             const LAS bf16x8* wb = (const LAS bf16x8*)(lds + L_WGF) + (size_t)((3 + mt) * 6) * 64 + lane;
; #pragma unroll
;             for (int s = 0; s < 5; ++s) { gr = MFMA32(wa[s * 64], xf[s], gr); gi = MFMA32(wb[s * 64], xf[s], gi); }
;             gr = MFMA32(wa[5 * 64], xone, gr); gi = MFMA32(wb[5 * 64], xone, gi);
;             __builtin_amdgcn_sched_barrier(0);
; #pragma unroll
;             for (int i4 = 0; i4 < 4; ++i4) { if (mt == 2 && i4 >= 2) continue;
;                 const int s = 2 * mt + (i4 >> 1), half = i4 & 1, ch0 = 16 * s + 8 * half + 4 * hh;
;                 const f32x4 ls2 = *(const LAS f32x4*)(par + 7 * LB + ch0);
;                 float A4[4], B4[4];
; #pragma unroll
;                 for (int q = 0; q < 4; ++q) { const int i = 4 * i4 + q;
;                     const float rg = rcpf_(1.0f + ex2(gr[i])), ig = rcpf_(1.0f + ex2(gi[i]));
;                     const float la2 = ls2[q] * rg, a = ex2(la2), xx = (2.0f * LN2) * la2;
;                     const float poly = -xx * (1.0f + xx * (0.5f + xx * ((1.0f / 6.0f) + xx * ((1.0f / 24.0f) + xx * (1.0f / 120.0f)))));
;                     const float om = (xx > -0.25f) ? poly : (1.0f - a * a);
.LBB0_304:
	s_or_b64 exec, exec, s[2:3]
	global_load_dwordx2 v[162:163], v[0:1], off offset:1024
	global_load_dwordx2 v[158:159], v[0:1], off offset:1536
	global_load_dwordx2 v[152:153], v[0:1], off offset:2048
	global_load_dwordx2 v[146:147], v[0:1], off offset:2560
	global_load_dwordx2 v[140:141], v[0:1], off offset:3072
	global_load_dwordx2 v[122:123], v[0:1], off offset:3584
	v_add_co_u32_e32 v2, vcc, s5, v0
	v_mov_b32_e32 v128, 0
	s_nop 0
	v_addc_co_u32_e32 v3, vcc, 0, v1, vcc
	global_load_dwordx2 v[174:175], v[0:1], off
	global_load_dwordx2 v[170:171], v[0:1], off offset:512
	global_load_dwordx2 v[120:121], v[2:3], off
	global_load_dwordx2 v[26:27], v[2:3], off offset:512
	v_mov_b32_e32 v0, 0x3f80
	v_cmp_gt_u32_e32 vcc, 32, v232
	v_mov_b32_e32 v1, v128
	s_mov_b64 s[2:3], 0x6000000
	v_cndmask_b32_e32 v32, 0, v0, vcc
	v_lshlrev_b32_e32 v0, 3, v232
	v_lshl_add_u64 v[0:1], s[54:55], 0, v[0:1]
	v_lshl_add_u64 v[130:131], v[0:1], 0, s[2:3]
	v_lshlrev_b32_e32 v0, 3, v184
	v_mov_b32_e32 v1, v128
	v_lshl_add_u64 v[0:1], s[54:55], 0, v[0:1]
	s_mov_b64 s[6:7], 0x130000
	s_add_u32 s16, s54, 0x8c00000
	v_lshrrev_b32_e32 v2, 5, v232
	s_mul_i32 s4, s63, 0x280
	v_lshl_add_u64 v[132:133], v[0:1], 0, s[6:7]
	v_and_or_b32 v1, v4, 31, v187
	s_addc_u32 s17, s55, 0
	v_lshlrev_b32_e32 v233, 4, v2
	s_add_i32 s27, s4, 0
	s_movk_i32 s4, 0x50
	s_mul_i32 s6, s63, 0xfffffec0
	v_lshlrev_b32_e32 v0, 3, v2
	v_lshlrev_b32_e32 v2, 3, v1
	v_mov_b32_e32 v3, v128
	v_add_u32_e32 v234, 0, v233
	v_mov_b32_e32 v33, v128
	v_mov_b32_e32 v34, v128
	v_mov_b32_e32 v35, v128
	v_cmp_eq_u32_e64 s[2:3], 31, v185
	v_add_u32_e32 v235, s26, v4
	v_cmp_gt_u32_e64 s[4:5], s4, v184
	v_lshl_add_u32 v236, v184, 2, 0
	s_add_i32 s28, s27, s6
	v_lshl_add_u32 v237, v232, 4, 0
	v_lshl_add_u64 v[134:135], s[10:11], 0, v[2:3]
	v_mov_b32_e32 v238, 0x3d2aaaab
	v_mov_b32_e32 v240, 1.0
	v_mov_b32_e32 v242, 0x3fb17218
	v_mov_b32_e32 v244, 0x3c088889
	v_mov_b32_e32 v246, 0x3e2aaaab
	v_mov_b32_e32 v248, 0.5
	s_mov_b32 s29, 0xbe800000
	s_mov_b32 s15, 1
	v_mov_b32_e32 v137, 1
	s_movk_i32 s30, 0xa00
	v_lshlrev_b32_e32 v138, 1, v0
	v_mov_b32_e32 v239, 0x280
	s_mov_b32 s20, s33
	s_waitcnt vmcnt(0)
	ds_write_b128 v70, v[44:47]
	ds_write_b128 v70, v[48:51] offset:8192
	ds_write_b128 v70, v[52:55] offset:16384
	ds_write_b128 v70, v[56:59] offset:24576
	s_and_saveexec_b64 s[94:95], s[96:97]
	s_cbranch_execz .Lp2_stage_c_a
	ds_write_b128 v70, v[60:63] offset:32768
.Lp2_stage_c_a:
	s_or_b64 exec, exec, s[94:95]
	s_and_saveexec_b64 s[94:95], s[98:99]
	s_cbranch_execz .Lp2_fin_a
	ds_write_b128 v70, v[66:69] offset:36864
.Lp2_fin_a:
	s_or_b64 exec, exec, s[94:95]
	s_waitcnt lgkmcnt(0)
	s_barrier
	s_branch .LBB0_308
.Lp2_nounit:
	s_waitcnt vmcnt(0)
	ds_write_b128 v70, v[44:47]
	ds_write_b128 v70, v[48:51] offset:8192
	ds_write_b128 v70, v[52:55] offset:16384
	ds_write_b128 v70, v[56:59] offset:24576
	s_and_saveexec_b64 s[94:95], s[96:97]
	s_cbranch_execz .Lp2_stage_c_b
	ds_write_b128 v70, v[60:63] offset:32768
